# hand-written short-conv fix-up before the out-projection: all halo rows of both panels loaded up front, packed-f32 math
# speedup vs baseline: 1.0170x; 1.0012x over previous
; __device__ __forceinline__ float bf_lo(unsigned w) { return __uint_as_float(w << 16); }
; __device__ __forceinline__ float bf_hi(unsigned w) { return __uint_as_float(w & 0xffff0000u); }
; __device__ __forceinline__ int otid() { int t = threadIdx.x; asm volatile("" : "+v"(t)); return t; }
;     __device__ __forceinline__ bool next(int i, Unit& u) const { const long L = (long)i * G + c; if (L >= NG * 8) return false; u.g = (int)(L >> 3); u.pm = (int)(L & 7); u.pn = 0; return true; }
;     __device__ __forceinline__ bool next(int i, Unit& u) const { if (i >= 2) return false; u.g = g; u.pm = 2 * b + i; u.pn = 0; return true; }
; template <int MODE, class Sched> __device__ __forceinline__ void fixup_local(const bf16_t* halo, const float* cw, const float* cb, bf16_t* out, int C, const Sched& S) {
;     const int C4 = C >> 2, tid = otid(); Unit u;
;     for (int i = 0; S.next(i, u); ++i)
;         for (int c4 = tid; c4 < C4; c4 += 512) {
;             const int c = c4 * 4;
;             const f32x4 w0 = *(const f32x4*)(cw + c), w1 = *(const f32x4*)(cw + C + c), w2 = *(const f32x4*)(cw + 2 * C + c);
;             f32x4 bb = (f32x4){0.f, 0.f, 0.f, 0.f}; if (MODE == 0) bb = *(const f32x4*)(cb + c);
;             f32x4 t0[4], t1[4], h0[4], h1[4], y0[4], y1[4];
; #pragma unroll
;             for (int k = 0; k < 4; ++k) { const int s = 4 * u.pm + k; const bf16_t* hb = halo + (size_t)s * 6 * C + c; const bool first = (s & 127) == 0;
;                 const f32x4 z = (f32x4){0.f, 0.f, 0.f, 0.f};
;                 auto ld4 = [](const bf16_t* ptr) { const u32x2 w = *(const u32x2*)ptr; return (f32x4){bf_lo(w.x), bf_hi(w.x), bf_lo(w.y), bf_hi(w.y)}; };
;                 t0[k] = ld4(first ? hb : hb - (size_t)6 * C); t1[k] = ld4(first ? hb : hb - (size_t)5 * C);
;                 if (first) { t0[k] = z; t1[k] = z; }
;                 h0[k] = ld4(hb + (size_t)2 * C); h1[k] = ld4(hb + (size_t)3 * C);
;                 y0[k] = ld4(hb + (size_t)4 * C); y1[k] = ld4(hb + (size_t)5 * C); }
.LBB0_892:
	s_or_b64 exec, exec, s[0:1]
	v_readlane_b32 s0, v252, 48
	v_readlane_b32 s1, v252, 49
	s_mov_b32 s2, s0
	s_add_u32 s0, s48, 0x1000
	s_addc_u32 s1, s49, 0
	s_mov_b32 s8, 4
	s_add_u32 s6, s48, 0x2000
	s_waitcnt lgkmcnt(0)
	s_barrier
	s_addc_u32 s7, s49, 0
	s_lshl_b32 s14, s8, 3
	s_abs_i32 s15, s14
	v_cvt_f32_u32_e32 v0, s15
	s_bfe_i32 s35, s8, 0x1001c
	s_sub_i32 s8, 0, s15
	v_mov_b32_e32 v1, v232
	v_rcp_iflag_f32_e32 v0, v0
	s_movk_i32 s4, 0x100
	s_ashr_i32 s33, s2, 31
	v_mul_f32_e32 v0, 0x4f7ffffe, v0
	v_cvt_u32_f32_e32 v0, v0
	v_cmp_gt_i32_e64 s[4:5], s4, v1
	s_mov_b32 s50, 0
	v_add_u32_e32 v44, 0xfffffe00, v1
	v_readfirstlane_b32 s9, v0
	s_mul_i32 s8, s8, s9
	s_mul_hi_u32 s8, s9, s8
	s_add_i32 s70, s9, s8
	v_lshlrev_b32_e32 v45, 2, v1
	v_mov_b64_e32 v[12:13], 0x1ff
	s_movk_i32 s22, 0xd000
	s_movk_i32 s23, 0x1000
	s_movk_i32 s51, 0x2000
	s_movk_i32 s52, 0xe000
	s_movk_i32 s53, 0xfeff
	s_cmp_lg_u32 s34, 0x100
	s_cbranch_scc1 .Lfixs_generic
	s_mov_b64 s[10:11], exec
	s_and_b64 exec, exec, s[4:5]
	s_cbranch_execz .Lfixs_end1
	v_lshlrev_b32_e32 v1, 3, v232
	v_lshlrev_b32_e32 v3, 4, v232
	s_and_b32 s16, s2, 7
	s_lshl_b32 s16, s16, 4
	s_bfe_u32 s17, s2, 0x30003
	s_add_i32 s16, s16, s17
	global_load_dwordx4 v[8:11], v3, s[48:49]
	global_load_dwordx4 v[12:15], v3, s[0:1]
	global_load_dwordx4 v[16:19], v3, s[6:7]
	s_add_i32 s17, s16, 0
	s_lshl_b32 s17, s17, 2
	s_mul_i32 s17, s17, 0x3000
	s_add_u32 s18, s42, s17
	s_addc_u32 s19, s43, 0
	s_add_i32 s17, s16, 0
	s_and_b32 s17, s17, 31
	s_cmp_eq_u32 s17, 0
	s_cselect_b32 s26, 0, 0x3000
	s_sub_u32 s24, s18, s26
	s_subb_u32 s25, s19, 0
	global_load_dwordx2 v[40:41], v1, s[24:25]
	global_load_dwordx2 v[42:43], v1, s[24:25] offset:2048
	s_add_u32 s24, s18, 0x1000
	s_addc_u32 s25, s19, 0
	global_load_dwordx2 v[44:45], v1, s[24:25]
	global_load_dwordx2 v[46:47], v1, s[24:25] offset:2048
	s_add_u32 s24, s18, 0x2000
	s_addc_u32 s25, s19, 0
	global_load_dwordx2 v[48:49], v1, s[24:25]
	global_load_dwordx2 v[50:51], v1, s[24:25] offset:2048
	s_add_i32 s17, s16, 0
	s_lshl_b32 s17, s17, 2
	s_add_i32 s17, s17, 1
	s_mul_i32 s17, s17, 0x3000
	s_add_u32 s18, s42, s17
	s_addc_u32 s19, s43, 0
	s_mov_b32 s26, 0x3000
	s_sub_u32 s24, s18, s26
	s_subb_u32 s25, s19, 0
	global_load_dwordx2 v[52:53], v1, s[24:25]
	global_load_dwordx2 v[54:55], v1, s[24:25] offset:2048
	s_add_u32 s24, s18, 0x1000
	s_addc_u32 s25, s19, 0
	global_load_dwordx2 v[56:57], v1, s[24:25]
	global_load_dwordx2 v[58:59], v1, s[24:25] offset:2048
	s_add_u32 s24, s18, 0x2000
	s_addc_u32 s25, s19, 0
	global_load_dwordx2 v[60:61], v1, s[24:25]
	global_load_dwordx2 v[62:63], v1, s[24:25] offset:2048
	s_add_i32 s17, s16, 0
	s_lshl_b32 s17, s17, 2
	s_add_i32 s17, s17, 2
	s_mul_i32 s17, s17, 0x3000
	s_add_u32 s18, s42, s17
	s_addc_u32 s19, s43, 0
	s_mov_b32 s26, 0x3000
	s_sub_u32 s24, s18, s26
	s_subb_u32 s25, s19, 0
	global_load_dwordx2 v[64:65], v1, s[24:25]
	global_load_dwordx2 v[66:67], v1, s[24:25] offset:2048
	s_add_u32 s24, s18, 0x1000
	s_addc_u32 s25, s19, 0
	global_load_dwordx2 v[68:69], v1, s[24:25]
	global_load_dwordx2 v[70:71], v1, s[24:25] offset:2048
	s_add_u32 s24, s18, 0x2000
	s_addc_u32 s25, s19, 0
	global_load_dwordx2 v[72:73], v1, s[24:25]
	global_load_dwordx2 v[74:75], v1, s[24:25] offset:2048
	s_add_i32 s17, s16, 0
	s_lshl_b32 s17, s17, 2
	s_add_i32 s17, s17, 3
	s_mul_i32 s17, s17, 0x3000
	s_add_u32 s18, s42, s17
	s_addc_u32 s19, s43, 0
	s_mov_b32 s26, 0x3000
	s_sub_u32 s24, s18, s26
	s_subb_u32 s25, s19, 0
	global_load_dwordx2 v[76:77], v1, s[24:25]
	global_load_dwordx2 v[78:79], v1, s[24:25] offset:2048
	s_add_u32 s24, s18, 0x1000
	s_addc_u32 s25, s19, 0
	global_load_dwordx2 v[80:81], v1, s[24:25]
	global_load_dwordx2 v[82:83], v1, s[24:25] offset:2048
	s_add_u32 s24, s18, 0x2000
	s_addc_u32 s25, s19, 0
	global_load_dwordx2 v[84:85], v1, s[24:25]
	global_load_dwordx2 v[86:87], v1, s[24:25] offset:2048
	s_add_i32 s17, s16, 8
	s_lshl_b32 s17, s17, 2
	s_mul_i32 s17, s17, 0x3000
	s_add_u32 s18, s42, s17
	s_addc_u32 s19, s43, 0
	s_add_i32 s17, s16, 8
	s_and_b32 s17, s17, 31
	s_cmp_eq_u32 s17, 0
	s_cselect_b32 s26, 0, 0x3000
	s_sub_u32 s24, s18, s26
	s_subb_u32 s25, s19, 0
	global_load_dwordx2 v[88:89], v1, s[24:25]
	global_load_dwordx2 v[90:91], v1, s[24:25] offset:2048
	s_add_u32 s24, s18, 0x1000
	s_addc_u32 s25, s19, 0
	global_load_dwordx2 v[92:93], v1, s[24:25]
	global_load_dwordx2 v[94:95], v1, s[24:25] offset:2048
	s_add_u32 s24, s18, 0x2000
	s_addc_u32 s25, s19, 0
	global_load_dwordx2 v[96:97], v1, s[24:25]
	global_load_dwordx2 v[98:99], v1, s[24:25] offset:2048
	s_add_i32 s17, s16, 8
	s_lshl_b32 s17, s17, 2
	s_add_i32 s17, s17, 1
	s_mul_i32 s17, s17, 0x3000
	s_add_u32 s18, s42, s17
	s_addc_u32 s19, s43, 0
	s_mov_b32 s26, 0x3000
	s_sub_u32 s24, s18, s26
	s_subb_u32 s25, s19, 0
	global_load_dwordx2 v[100:101], v1, s[24:25]
	global_load_dwordx2 v[102:103], v1, s[24:25] offset:2048
	s_add_u32 s24, s18, 0x1000
	s_addc_u32 s25, s19, 0
	global_load_dwordx2 v[104:105], v1, s[24:25]
	global_load_dwordx2 v[106:107], v1, s[24:25] offset:2048
	s_add_u32 s24, s18, 0x2000
	s_addc_u32 s25, s19, 0
	global_load_dwordx2 v[108:109], v1, s[24:25]
	global_load_dwordx2 v[110:111], v1, s[24:25] offset:2048
	s_add_i32 s17, s16, 8
	s_lshl_b32 s17, s17, 2
	s_add_i32 s17, s17, 2
	s_mul_i32 s17, s17, 0x3000
	s_add_u32 s18, s42, s17
	s_addc_u32 s19, s43, 0
	s_mov_b32 s26, 0x3000
	s_sub_u32 s24, s18, s26
	s_subb_u32 s25, s19, 0
	global_load_dwordx2 v[112:113], v1, s[24:25]
	global_load_dwordx2 v[114:115], v1, s[24:25] offset:2048
	s_add_u32 s24, s18, 0x1000
	s_addc_u32 s25, s19, 0
	global_load_dwordx2 v[116:117], v1, s[24:25]
	global_load_dwordx2 v[118:119], v1, s[24:25] offset:2048
	s_add_u32 s24, s18, 0x2000
	s_addc_u32 s25, s19, 0
	global_load_dwordx2 v[120:121], v1, s[24:25]
	global_load_dwordx2 v[122:123], v1, s[24:25] offset:2048
	s_add_i32 s17, s16, 8
	s_lshl_b32 s17, s17, 2
	s_add_i32 s17, s17, 3
	s_mul_i32 s17, s17, 0x3000
	s_add_u32 s18, s42, s17
	s_addc_u32 s19, s43, 0
	s_mov_b32 s26, 0x3000
	s_sub_u32 s24, s18, s26
	s_subb_u32 s25, s19, 0
	global_load_dwordx2 v[124:125], v1, s[24:25]
	global_load_dwordx2 v[126:127], v1, s[24:25] offset:2048
	s_add_u32 s24, s18, 0x1000
	s_addc_u32 s25, s19, 0
	global_load_dwordx2 v[128:129], v1, s[24:25]
	global_load_dwordx2 v[130:131], v1, s[24:25] offset:2048
	s_add_u32 s24, s18, 0x2000
	s_addc_u32 s25, s19, 0
	global_load_dwordx2 v[132:133], v1, s[24:25]
	global_load_dwordx2 v[134:135], v1, s[24:25] offset:2048
	s_waitcnt vmcnt(24)
	s_add_i32 s17, s16, 0
	s_and_b32 s17, s17, 31
	s_cmp_lg_u32 s17, 0
	s_cbranch_scc1 .Lfixs_nz2
	v_mov_b32_e32 v40, 0
	v_mov_b32_e32 v41, 0
	v_mov_b32_e32 v42, 0
	v_mov_b32_e32 v43, 0
; __device__ __forceinline__ unsigned cvt_pk_bf16(float lo, float hi) { unsigned r; asm volatile("v_cvt_pk_bf16_f32 %0, %1, %2" : "=v"(r) : "v"(lo), "v"(hi)); return r; }
; __device__ __forceinline__ float silu_f(float x) { return x * __builtin_amdgcn_rcpf(1.0f + __builtin_amdgcn_exp2f(x * -1.44269504f)); }
; template <int MODE, class Sched> __device__ __forceinline__ void fixup_local(const bf16_t* halo, const float* cw, const float* cb, bf16_t* out, int C, const Sched& S) {
;     ...
;             for (int k = 0; k < 4; ++k) { const int s = 4 * u.pm + k; float o0[4], o1[4];
; #pragma unroll
;                 for (int j = 0; j < 4; ++j) {
;                     const float cv0 = w2[j] * h0[k][j] + w1[j] * t1[k][j] + w0[j] * t0[k][j] + bb[j];
;                     const float cv1 = w2[j] * h1[k][j] + w1[j] * h0[k][j] + w0[j] * t1[k][j] + bb[j];
;                     o0[j] = MODE == 0 ? silu_f(cv0) * y0[k][j] : cv0 * y0[k][j]; o1[j] = MODE == 0 ? silu_f(cv1) * y1[k][j] : cv1 * y1[k][j]; }
;                 u32x2 a; a.x = cvt_pk_bf16(o0[0], o0[1]); a.y = cvt_pk_bf16(o0[2], o0[3]); u32x2 b; b.x = cvt_pk_bf16(o1[0], o1[1]); b.y = cvt_pk_bf16(o1[2], o1[3]);
;                 *(u32x2*)(out + ((size_t)s * 64) * C + c) = a; *(u32x2*)(out + ((size_t)s * 64 + 1) * C + c) = b; }
.Lfixs_nz2:
	v_lshlrev_b32_e32 v136, 16, v41
	v_and_b32_e32 v137, 0xffff0000, v41
	v_and_b32_e32 v41, 0xffff0000, v40
	v_lshlrev_b32_e32 v40, 16, v40
	v_lshlrev_b32_e32 v138, 16, v43
	v_and_b32_e32 v139, 0xffff0000, v43
	v_and_b32_e32 v43, 0xffff0000, v42
	v_lshlrev_b32_e32 v42, 16, v42
	v_lshlrev_b32_e32 v140, 16, v45
	v_and_b32_e32 v141, 0xffff0000, v45
	v_and_b32_e32 v45, 0xffff0000, v44
	v_lshlrev_b32_e32 v44, 16, v44
	v_lshlrev_b32_e32 v142, 16, v47
	v_and_b32_e32 v143, 0xffff0000, v47
	v_and_b32_e32 v47, 0xffff0000, v46
	v_lshlrev_b32_e32 v46, 16, v46
	v_lshlrev_b32_e32 v144, 16, v49
	v_and_b32_e32 v145, 0xffff0000, v49
	v_and_b32_e32 v49, 0xffff0000, v48
	v_lshlrev_b32_e32 v48, 16, v48
	v_lshlrev_b32_e32 v146, 16, v51
	v_and_b32_e32 v147, 0xffff0000, v51
	v_and_b32_e32 v51, 0xffff0000, v50
	v_lshlrev_b32_e32 v50, 16, v50
	v_pk_mul_f32 v[148:149], v[16:17], v[44:45]
	v_pk_mul_f32 v[150:151], v[18:19], v[140:141]
	v_pk_mul_f32 v[152:153], v[16:17], v[46:47]
	v_pk_mul_f32 v[154:155], v[18:19], v[142:143]
	v_pk_fma_f32 v[148:149], v[12:13], v[42:43], v[148:149]
	v_pk_fma_f32 v[150:151], v[14:15], v[138:139], v[150:151]
	v_pk_fma_f32 v[152:153], v[12:13], v[44:45], v[152:153]
	v_pk_fma_f32 v[154:155], v[14:15], v[140:141], v[154:155]
	v_pk_fma_f32 v[148:149], v[8:9], v[40:41], v[148:149]
	v_pk_fma_f32 v[150:151], v[10:11], v[136:137], v[150:151]
	v_pk_fma_f32 v[152:153], v[8:9], v[42:43], v[152:153]
	v_pk_fma_f32 v[154:155], v[10:11], v[138:139], v[154:155]
	v_pk_mul_f32 v[148:149], v[148:149], v[48:49]
	v_pk_mul_f32 v[150:151], v[150:151], v[144:145]
	v_pk_mul_f32 v[152:153], v[152:153], v[50:51]
	v_pk_mul_f32 v[154:155], v[154:155], v[146:147]
	v_cvt_pk_bf16_f32 v164, v148, v149
	v_cvt_pk_bf16_f32 v165, v150, v151
	v_cvt_pk_bf16_f32 v166, v152, v153
	v_cvt_pk_bf16_f32 v167, v154, v155
	s_add_i32 s17, s16, 0
	s_lshl_b32 s17, s17, 2
	s_lshl_b32 s17, s17, 17
	s_add_u32 s36, s40, s17
	s_addc_u32 s37, s41, 0
	global_store_dwordx2 v1, v[164:165], s[36:37]
	global_store_dwordx2 v1, v[166:167], s[36:37] offset:2048
	v_lshlrev_b32_e32 v136, 16, v53
	v_and_b32_e32 v137, 0xffff0000, v53
	v_and_b32_e32 v53, 0xffff0000, v52
	v_lshlrev_b32_e32 v52, 16, v52
	v_lshlrev_b32_e32 v138, 16, v55
	v_and_b32_e32 v139, 0xffff0000, v55
	v_and_b32_e32 v55, 0xffff0000, v54
	v_lshlrev_b32_e32 v54, 16, v54
	v_lshlrev_b32_e32 v140, 16, v57
	v_and_b32_e32 v141, 0xffff0000, v57
	v_and_b32_e32 v57, 0xffff0000, v56
	v_lshlrev_b32_e32 v56, 16, v56
	v_lshlrev_b32_e32 v142, 16, v59
	v_and_b32_e32 v143, 0xffff0000, v59
	v_and_b32_e32 v59, 0xffff0000, v58
	v_lshlrev_b32_e32 v58, 16, v58
	v_lshlrev_b32_e32 v144, 16, v61
	v_and_b32_e32 v145, 0xffff0000, v61
	v_and_b32_e32 v61, 0xffff0000, v60
	v_lshlrev_b32_e32 v60, 16, v60
	v_lshlrev_b32_e32 v146, 16, v63
	v_and_b32_e32 v147, 0xffff0000, v63
	v_and_b32_e32 v63, 0xffff0000, v62
	v_lshlrev_b32_e32 v62, 16, v62
	v_pk_mul_f32 v[148:149], v[16:17], v[56:57]
	v_pk_mul_f32 v[150:151], v[18:19], v[140:141]
	v_pk_mul_f32 v[152:153], v[16:17], v[58:59]
	v_pk_mul_f32 v[154:155], v[18:19], v[142:143]
	v_pk_fma_f32 v[148:149], v[12:13], v[54:55], v[148:149]
	v_pk_fma_f32 v[150:151], v[14:15], v[138:139], v[150:151]
	v_pk_fma_f32 v[152:153], v[12:13], v[56:57], v[152:153]
	v_pk_fma_f32 v[154:155], v[14:15], v[140:141], v[154:155]
	v_pk_fma_f32 v[148:149], v[8:9], v[52:53], v[148:149]
	v_pk_fma_f32 v[150:151], v[10:11], v[136:137], v[150:151]
	v_pk_fma_f32 v[152:153], v[8:9], v[54:55], v[152:153]
	v_pk_fma_f32 v[154:155], v[10:11], v[138:139], v[154:155]
	v_pk_mul_f32 v[148:149], v[148:149], v[60:61]
	v_pk_mul_f32 v[150:151], v[150:151], v[144:145]
	v_pk_mul_f32 v[152:153], v[152:153], v[62:63]
	v_pk_mul_f32 v[154:155], v[154:155], v[146:147]
	v_cvt_pk_bf16_f32 v164, v148, v149
	v_cvt_pk_bf16_f32 v165, v150, v151
	v_cvt_pk_bf16_f32 v166, v152, v153
	v_cvt_pk_bf16_f32 v167, v154, v155
	s_add_i32 s17, s16, 0
	s_lshl_b32 s17, s17, 2
	s_add_i32 s17, s17, 1
	s_lshl_b32 s17, s17, 17
	s_add_u32 s36, s40, s17
	s_addc_u32 s37, s41, 0
	global_store_dwordx2 v1, v[164:165], s[36:37]
	global_store_dwordx2 v1, v[166:167], s[36:37] offset:2048
	v_lshlrev_b32_e32 v136, 16, v65
	v_and_b32_e32 v137, 0xffff0000, v65
	v_and_b32_e32 v65, 0xffff0000, v64
	v_lshlrev_b32_e32 v64, 16, v64
	v_lshlrev_b32_e32 v138, 16, v67
	v_and_b32_e32 v139, 0xffff0000, v67
	v_and_b32_e32 v67, 0xffff0000, v66
	v_lshlrev_b32_e32 v66, 16, v66
	v_lshlrev_b32_e32 v140, 16, v69
	v_and_b32_e32 v141, 0xffff0000, v69
	v_and_b32_e32 v69, 0xffff0000, v68
	v_lshlrev_b32_e32 v68, 16, v68
	v_lshlrev_b32_e32 v142, 16, v71
	v_and_b32_e32 v143, 0xffff0000, v71
	v_and_b32_e32 v71, 0xffff0000, v70
	v_lshlrev_b32_e32 v70, 16, v70
	v_lshlrev_b32_e32 v144, 16, v73
	v_and_b32_e32 v145, 0xffff0000, v73
	v_and_b32_e32 v73, 0xffff0000, v72
	v_lshlrev_b32_e32 v72, 16, v72
	v_lshlrev_b32_e32 v146, 16, v75
	v_and_b32_e32 v147, 0xffff0000, v75
	v_and_b32_e32 v75, 0xffff0000, v74
	v_lshlrev_b32_e32 v74, 16, v74
	v_pk_mul_f32 v[148:149], v[16:17], v[68:69]
	v_pk_mul_f32 v[150:151], v[18:19], v[140:141]
	v_pk_mul_f32 v[152:153], v[16:17], v[70:71]
	v_pk_mul_f32 v[154:155], v[18:19], v[142:143]
	v_pk_fma_f32 v[148:149], v[12:13], v[66:67], v[148:149]
	v_pk_fma_f32 v[150:151], v[14:15], v[138:139], v[150:151]
	v_pk_fma_f32 v[152:153], v[12:13], v[68:69], v[152:153]
	v_pk_fma_f32 v[154:155], v[14:15], v[140:141], v[154:155]
	v_pk_fma_f32 v[148:149], v[8:9], v[64:65], v[148:149]
	v_pk_fma_f32 v[150:151], v[10:11], v[136:137], v[150:151]
	v_pk_fma_f32 v[152:153], v[8:9], v[66:67], v[152:153]
	v_pk_fma_f32 v[154:155], v[10:11], v[138:139], v[154:155]
	v_pk_mul_f32 v[148:149], v[148:149], v[72:73]
; __device__ __forceinline__ unsigned cvt_pk_bf16(float lo, float hi) { unsigned r; asm volatile("v_cvt_pk_bf16_f32 %0, %1, %2" : "=v"(r) : "v"(lo), "v"(hi)); return r; }
; __device__ __forceinline__ float bf_lo(unsigned w) { return __uint_as_float(w << 16); }
; __device__ __forceinline__ float bf_hi(unsigned w) { return __uint_as_float(w & 0xffff0000u); }
; __device__ __forceinline__ float silu_f(float x) { return x * __builtin_amdgcn_rcpf(1.0f + __builtin_amdgcn_exp2f(x * -1.44269504f)); }
; template <int MODE, class Sched> __device__ __forceinline__ void fixup_local(const bf16_t* halo, const float* cw, const float* cb, bf16_t* out, int C, const Sched& S) {
;     ...
;             for (int k = 0; k < 4; ++k) { const int s = 4 * u.pm + k; const bf16_t* hb = halo + (size_t)s * 6 * C + c; const bool first = (s & 127) == 0;
;                 const f32x4 z = (f32x4){0.f, 0.f, 0.f, 0.f};
;                 auto ld4 = [](const bf16_t* ptr) { const u32x2 w = *(const u32x2*)ptr; return (f32x4){bf_lo(w.x), bf_hi(w.x), bf_lo(w.y), bf_hi(w.y)}; };
;                 t0[k] = ld4(first ? hb : hb - (size_t)6 * C); t1[k] = ld4(first ? hb : hb - (size_t)5 * C);
;                 if (first) { t0[k] = z; t1[k] = z; }
;                 h0[k] = ld4(hb + (size_t)2 * C); h1[k] = ld4(hb + (size_t)3 * C);
;                 y0[k] = ld4(hb + (size_t)4 * C); y1[k] = ld4(hb + (size_t)5 * C); }
; #pragma unroll
;             for (int k = 0; k < 4; ++k) { const int s = 4 * u.pm + k; float o0[4], o1[4];
; #pragma unroll
;                 for (int j = 0; j < 4; ++j) {
;                     const float cv0 = w2[j] * h0[k][j] + w1[j] * t1[k][j] + w0[j] * t0[k][j] + bb[j];
;                     const float cv1 = w2[j] * h1[k][j] + w1[j] * h0[k][j] + w0[j] * t1[k][j] + bb[j];
;                     o0[j] = MODE == 0 ? silu_f(cv0) * y0[k][j] : cv0 * y0[k][j]; o1[j] = MODE == 0 ? silu_f(cv1) * y1[k][j] : cv1 * y1[k][j]; }
;                 u32x2 a; a.x = cvt_pk_bf16(o0[0], o0[1]); a.y = cvt_pk_bf16(o0[2], o0[3]); u32x2 b; b.x = cvt_pk_bf16(o1[0], o1[1]); b.y = cvt_pk_bf16(o1[2], o1[3]);
;                 *(u32x2*)(out + ((size_t)s * 64) * C + c) = a; *(u32x2*)(out + ((size_t)s * 64 + 1) * C + c) = b; }
	v_pk_mul_f32 v[150:151], v[150:151], v[144:145]
	v_pk_mul_f32 v[152:153], v[152:153], v[74:75]
	v_pk_mul_f32 v[154:155], v[154:155], v[146:147]
	v_cvt_pk_bf16_f32 v164, v148, v149
	v_cvt_pk_bf16_f32 v165, v150, v151
	v_cvt_pk_bf16_f32 v166, v152, v153
	v_cvt_pk_bf16_f32 v167, v154, v155
	s_add_i32 s17, s16, 0
	s_lshl_b32 s17, s17, 2
	s_add_i32 s17, s17, 2
	s_lshl_b32 s17, s17, 17
	s_add_u32 s36, s40, s17
	s_addc_u32 s37, s41, 0
	global_store_dwordx2 v1, v[164:165], s[36:37]
	global_store_dwordx2 v1, v[166:167], s[36:37] offset:2048
	v_lshlrev_b32_e32 v136, 16, v77
	v_and_b32_e32 v137, 0xffff0000, v77
	v_and_b32_e32 v77, 0xffff0000, v76
	v_lshlrev_b32_e32 v76, 16, v76
	v_lshlrev_b32_e32 v138, 16, v79
	v_and_b32_e32 v139, 0xffff0000, v79
	v_and_b32_e32 v79, 0xffff0000, v78
	v_lshlrev_b32_e32 v78, 16, v78
	v_lshlrev_b32_e32 v140, 16, v81
	v_and_b32_e32 v141, 0xffff0000, v81
	v_and_b32_e32 v81, 0xffff0000, v80
	v_lshlrev_b32_e32 v80, 16, v80
	v_lshlrev_b32_e32 v142, 16, v83
	v_and_b32_e32 v143, 0xffff0000, v83
	v_and_b32_e32 v83, 0xffff0000, v82
	v_lshlrev_b32_e32 v82, 16, v82
	v_lshlrev_b32_e32 v144, 16, v85
	v_and_b32_e32 v145, 0xffff0000, v85
	v_and_b32_e32 v85, 0xffff0000, v84
	v_lshlrev_b32_e32 v84, 16, v84
	v_lshlrev_b32_e32 v146, 16, v87
	v_and_b32_e32 v147, 0xffff0000, v87
	v_and_b32_e32 v87, 0xffff0000, v86
	v_lshlrev_b32_e32 v86, 16, v86
	v_pk_mul_f32 v[148:149], v[16:17], v[80:81]
	v_pk_mul_f32 v[150:151], v[18:19], v[140:141]
	v_pk_mul_f32 v[152:153], v[16:17], v[82:83]
	v_pk_mul_f32 v[154:155], v[18:19], v[142:143]
	v_pk_fma_f32 v[148:149], v[12:13], v[78:79], v[148:149]
	v_pk_fma_f32 v[150:151], v[14:15], v[138:139], v[150:151]
	v_pk_fma_f32 v[152:153], v[12:13], v[80:81], v[152:153]
	v_pk_fma_f32 v[154:155], v[14:15], v[140:141], v[154:155]
	v_pk_fma_f32 v[148:149], v[8:9], v[76:77], v[148:149]
	v_pk_fma_f32 v[150:151], v[10:11], v[136:137], v[150:151]
	v_pk_fma_f32 v[152:153], v[8:9], v[78:79], v[152:153]
	v_pk_fma_f32 v[154:155], v[10:11], v[138:139], v[154:155]
	v_pk_mul_f32 v[148:149], v[148:149], v[84:85]
	v_pk_mul_f32 v[150:151], v[150:151], v[144:145]
	v_pk_mul_f32 v[152:153], v[152:153], v[86:87]
	v_pk_mul_f32 v[154:155], v[154:155], v[146:147]
	v_cvt_pk_bf16_f32 v164, v148, v149
	v_cvt_pk_bf16_f32 v165, v150, v151
	v_cvt_pk_bf16_f32 v166, v152, v153
	v_cvt_pk_bf16_f32 v167, v154, v155
	s_add_i32 s17, s16, 0
	s_lshl_b32 s17, s17, 2
	s_add_i32 s17, s17, 3
	s_lshl_b32 s17, s17, 17
	s_add_u32 s36, s40, s17
	s_addc_u32 s37, s41, 0
	global_store_dwordx2 v1, v[164:165], s[36:37]
	global_store_dwordx2 v1, v[166:167], s[36:37] offset:2048
	s_waitcnt vmcnt(8)
	s_add_i32 s17, s16, 8
	s_and_b32 s17, s17, 31
	s_cmp_lg_u32 s17, 0
	s_cbranch_scc1 .Lfixs_nz3
	v_mov_b32_e32 v88, 0
	v_mov_b32_e32 v89, 0
	v_mov_b32_e32 v90, 0
	v_mov_b32_e32 v91, 0
.Lfixs_nz3:
	v_lshlrev_b32_e32 v136, 16, v89
	v_and_b32_e32 v137, 0xffff0000, v89
	v_and_b32_e32 v89, 0xffff0000, v88
	v_lshlrev_b32_e32 v88, 16, v88
	v_lshlrev_b32_e32 v138, 16, v91
	v_and_b32_e32 v139, 0xffff0000, v91
	v_and_b32_e32 v91, 0xffff0000, v90
	v_lshlrev_b32_e32 v90, 16, v90
	v_lshlrev_b32_e32 v140, 16, v93
	v_and_b32_e32 v141, 0xffff0000, v93
	v_and_b32_e32 v93, 0xffff0000, v92
	v_lshlrev_b32_e32 v92, 16, v92
	v_lshlrev_b32_e32 v142, 16, v95
	v_and_b32_e32 v143, 0xffff0000, v95
	v_and_b32_e32 v95, 0xffff0000, v94
	v_lshlrev_b32_e32 v94, 16, v94
	v_lshlrev_b32_e32 v144, 16, v97
	v_and_b32_e32 v145, 0xffff0000, v97
	v_and_b32_e32 v97, 0xffff0000, v96
	v_lshlrev_b32_e32 v96, 16, v96
	v_lshlrev_b32_e32 v146, 16, v99
	v_and_b32_e32 v147, 0xffff0000, v99
	v_and_b32_e32 v99, 0xffff0000, v98
	v_lshlrev_b32_e32 v98, 16, v98
	v_pk_mul_f32 v[148:149], v[16:17], v[92:93]
	v_pk_mul_f32 v[150:151], v[18:19], v[140:141]
	v_pk_mul_f32 v[152:153], v[16:17], v[94:95]
	v_pk_mul_f32 v[154:155], v[18:19], v[142:143]
	v_pk_fma_f32 v[148:149], v[12:13], v[90:91], v[148:149]
	v_pk_fma_f32 v[150:151], v[14:15], v[138:139], v[150:151]
	v_pk_fma_f32 v[152:153], v[12:13], v[92:93], v[152:153]
	v_pk_fma_f32 v[154:155], v[14:15], v[140:141], v[154:155]
	v_pk_fma_f32 v[148:149], v[8:9], v[88:89], v[148:149]
	v_pk_fma_f32 v[150:151], v[10:11], v[136:137], v[150:151]
	v_pk_fma_f32 v[152:153], v[8:9], v[90:91], v[152:153]
	v_pk_fma_f32 v[154:155], v[10:11], v[138:139], v[154:155]
	v_pk_mul_f32 v[148:149], v[148:149], v[96:97]
	v_pk_mul_f32 v[150:151], v[150:151], v[144:145]
	v_pk_mul_f32 v[152:153], v[152:153], v[98:99]
	v_pk_mul_f32 v[154:155], v[154:155], v[146:147]
	v_cvt_pk_bf16_f32 v164, v148, v149
	v_cvt_pk_bf16_f32 v165, v150, v151
	v_cvt_pk_bf16_f32 v166, v152, v153
	v_cvt_pk_bf16_f32 v167, v154, v155
	s_add_i32 s17, s16, 8
	s_lshl_b32 s17, s17, 2
	s_lshl_b32 s17, s17, 17
	s_add_u32 s36, s40, s17
	s_addc_u32 s37, s41, 0
	global_store_dwordx2 v1, v[164:165], s[36:37]
	global_store_dwordx2 v1, v[166:167], s[36:37] offset:2048
	v_lshlrev_b32_e32 v136, 16, v101
	v_and_b32_e32 v137, 0xffff0000, v101
	v_and_b32_e32 v101, 0xffff0000, v100
	v_lshlrev_b32_e32 v100, 16, v100
	v_lshlrev_b32_e32 v138, 16, v103
	v_and_b32_e32 v139, 0xffff0000, v103
	v_and_b32_e32 v103, 0xffff0000, v102
	v_lshlrev_b32_e32 v102, 16, v102
	v_lshlrev_b32_e32 v140, 16, v105
	v_and_b32_e32 v141, 0xffff0000, v105
	v_and_b32_e32 v105, 0xffff0000, v104
	v_lshlrev_b32_e32 v104, 16, v104
	v_lshlrev_b32_e32 v142, 16, v107
	v_and_b32_e32 v143, 0xffff0000, v107
	v_and_b32_e32 v107, 0xffff0000, v106
	v_lshlrev_b32_e32 v106, 16, v106
	v_lshlrev_b32_e32 v144, 16, v109
	v_and_b32_e32 v145, 0xffff0000, v109
	v_and_b32_e32 v109, 0xffff0000, v108
	v_lshlrev_b32_e32 v108, 16, v108
	v_lshlrev_b32_e32 v146, 16, v111
; __device__ __forceinline__ unsigned cvt_pk_bf16(float lo, float hi) { unsigned r; asm volatile("v_cvt_pk_bf16_f32 %0, %1, %2" : "=v"(r) : "v"(lo), "v"(hi)); return r; }
; __device__ __forceinline__ float silu_f(float x) { return x * __builtin_amdgcn_rcpf(1.0f + __builtin_amdgcn_exp2f(x * -1.44269504f)); }
; template <int MODE, class Sched> __device__ __forceinline__ void fixup_local(const bf16_t* halo, const float* cw, const float* cb, bf16_t* out, int C, const Sched& S) {
;     ...
;             for (int k = 0; k < 4; ++k) { const int s = 4 * u.pm + k; float o0[4], o1[4];
; #pragma unroll
;                 for (int j = 0; j < 4; ++j) {
;                     const float cv0 = w2[j] * h0[k][j] + w1[j] * t1[k][j] + w0[j] * t0[k][j] + bb[j];
;                     const float cv1 = w2[j] * h1[k][j] + w1[j] * h0[k][j] + w0[j] * t1[k][j] + bb[j];
;                     o0[j] = MODE == 0 ? silu_f(cv0) * y0[k][j] : cv0 * y0[k][j]; o1[j] = MODE == 0 ? silu_f(cv1) * y1[k][j] : cv1 * y1[k][j]; }
;                 u32x2 a; a.x = cvt_pk_bf16(o0[0], o0[1]); a.y = cvt_pk_bf16(o0[2], o0[3]); u32x2 b; b.x = cvt_pk_bf16(o1[0], o1[1]); b.y = cvt_pk_bf16(o1[2], o1[3]);
;                 *(u32x2*)(out + ((size_t)s * 64) * C + c) = a; *(u32x2*)(out + ((size_t)s * 64 + 1) * C + c) = b; }
	v_and_b32_e32 v147, 0xffff0000, v111
	v_and_b32_e32 v111, 0xffff0000, v110
	v_lshlrev_b32_e32 v110, 16, v110
	v_pk_mul_f32 v[148:149], v[16:17], v[104:105]
	v_pk_mul_f32 v[150:151], v[18:19], v[140:141]
	v_pk_mul_f32 v[152:153], v[16:17], v[106:107]
	v_pk_mul_f32 v[154:155], v[18:19], v[142:143]
	v_pk_fma_f32 v[148:149], v[12:13], v[102:103], v[148:149]
	v_pk_fma_f32 v[150:151], v[14:15], v[138:139], v[150:151]
	v_pk_fma_f32 v[152:153], v[12:13], v[104:105], v[152:153]
	v_pk_fma_f32 v[154:155], v[14:15], v[140:141], v[154:155]
	v_pk_fma_f32 v[148:149], v[8:9], v[100:101], v[148:149]
	v_pk_fma_f32 v[150:151], v[10:11], v[136:137], v[150:151]
	v_pk_fma_f32 v[152:153], v[8:9], v[102:103], v[152:153]
	v_pk_fma_f32 v[154:155], v[10:11], v[138:139], v[154:155]
	v_pk_mul_f32 v[148:149], v[148:149], v[108:109]
	v_pk_mul_f32 v[150:151], v[150:151], v[144:145]
	v_pk_mul_f32 v[152:153], v[152:153], v[110:111]
	v_pk_mul_f32 v[154:155], v[154:155], v[146:147]
	v_cvt_pk_bf16_f32 v164, v148, v149
	v_cvt_pk_bf16_f32 v165, v150, v151
	v_cvt_pk_bf16_f32 v166, v152, v153
	v_cvt_pk_bf16_f32 v167, v154, v155
	s_add_i32 s17, s16, 8
	s_lshl_b32 s17, s17, 2
	s_add_i32 s17, s17, 1
	s_lshl_b32 s17, s17, 17
	s_add_u32 s36, s40, s17
	s_addc_u32 s37, s41, 0
	global_store_dwordx2 v1, v[164:165], s[36:37]
	global_store_dwordx2 v1, v[166:167], s[36:37] offset:2048
	v_lshlrev_b32_e32 v136, 16, v113
	v_and_b32_e32 v137, 0xffff0000, v113
	v_and_b32_e32 v113, 0xffff0000, v112
	v_lshlrev_b32_e32 v112, 16, v112
	v_lshlrev_b32_e32 v138, 16, v115
	v_and_b32_e32 v139, 0xffff0000, v115
	v_and_b32_e32 v115, 0xffff0000, v114
	v_lshlrev_b32_e32 v114, 16, v114
	v_lshlrev_b32_e32 v140, 16, v117
	v_and_b32_e32 v141, 0xffff0000, v117
	v_and_b32_e32 v117, 0xffff0000, v116
	v_lshlrev_b32_e32 v116, 16, v116
	v_lshlrev_b32_e32 v142, 16, v119
	v_and_b32_e32 v143, 0xffff0000, v119
	v_and_b32_e32 v119, 0xffff0000, v118
	v_lshlrev_b32_e32 v118, 16, v118
	v_lshlrev_b32_e32 v144, 16, v121
	v_and_b32_e32 v145, 0xffff0000, v121
	v_and_b32_e32 v121, 0xffff0000, v120
	v_lshlrev_b32_e32 v120, 16, v120
	v_lshlrev_b32_e32 v146, 16, v123
	v_and_b32_e32 v147, 0xffff0000, v123
	v_and_b32_e32 v123, 0xffff0000, v122
	v_lshlrev_b32_e32 v122, 16, v122
	v_pk_mul_f32 v[148:149], v[16:17], v[116:117]
	v_pk_mul_f32 v[150:151], v[18:19], v[140:141]
	v_pk_mul_f32 v[152:153], v[16:17], v[118:119]
	v_pk_mul_f32 v[154:155], v[18:19], v[142:143]
	v_pk_fma_f32 v[148:149], v[12:13], v[114:115], v[148:149]
	v_pk_fma_f32 v[150:151], v[14:15], v[138:139], v[150:151]
	v_pk_fma_f32 v[152:153], v[12:13], v[116:117], v[152:153]
	v_pk_fma_f32 v[154:155], v[14:15], v[140:141], v[154:155]
	v_pk_fma_f32 v[148:149], v[8:9], v[112:113], v[148:149]
	v_pk_fma_f32 v[150:151], v[10:11], v[136:137], v[150:151]
	v_pk_fma_f32 v[152:153], v[8:9], v[114:115], v[152:153]
	v_pk_fma_f32 v[154:155], v[10:11], v[138:139], v[154:155]
	v_pk_mul_f32 v[148:149], v[148:149], v[120:121]
	v_pk_mul_f32 v[150:151], v[150:151], v[144:145]
	v_pk_mul_f32 v[152:153], v[152:153], v[122:123]
	v_pk_mul_f32 v[154:155], v[154:155], v[146:147]
	v_cvt_pk_bf16_f32 v164, v148, v149
	v_cvt_pk_bf16_f32 v165, v150, v151
	v_cvt_pk_bf16_f32 v166, v152, v153
	v_cvt_pk_bf16_f32 v167, v154, v155
	s_add_i32 s17, s16, 8
	s_lshl_b32 s17, s17, 2
	s_add_i32 s17, s17, 2
	s_lshl_b32 s17, s17, 17
	s_add_u32 s36, s40, s17
	s_addc_u32 s37, s41, 0
	global_store_dwordx2 v1, v[164:165], s[36:37]
	global_store_dwordx2 v1, v[166:167], s[36:37] offset:2048
	v_lshlrev_b32_e32 v136, 16, v125
	v_and_b32_e32 v137, 0xffff0000, v125
	v_and_b32_e32 v125, 0xffff0000, v124
	v_lshlrev_b32_e32 v124, 16, v124
	v_lshlrev_b32_e32 v138, 16, v127
	v_and_b32_e32 v139, 0xffff0000, v127
	v_and_b32_e32 v127, 0xffff0000, v126
	v_lshlrev_b32_e32 v126, 16, v126
	v_lshlrev_b32_e32 v140, 16, v129
	v_and_b32_e32 v141, 0xffff0000, v129
	v_and_b32_e32 v129, 0xffff0000, v128
	v_lshlrev_b32_e32 v128, 16, v128
	v_lshlrev_b32_e32 v142, 16, v131
	v_and_b32_e32 v143, 0xffff0000, v131
	v_and_b32_e32 v131, 0xffff0000, v130
	v_lshlrev_b32_e32 v130, 16, v130
	v_lshlrev_b32_e32 v144, 16, v133
	v_and_b32_e32 v145, 0xffff0000, v133
	v_and_b32_e32 v133, 0xffff0000, v132
	v_lshlrev_b32_e32 v132, 16, v132
	v_lshlrev_b32_e32 v146, 16, v135
	v_and_b32_e32 v147, 0xffff0000, v135
	v_and_b32_e32 v135, 0xffff0000, v134
	v_lshlrev_b32_e32 v134, 16, v134
	v_pk_mul_f32 v[148:149], v[16:17], v[128:129]
	v_pk_mul_f32 v[150:151], v[18:19], v[140:141]
	v_pk_mul_f32 v[152:153], v[16:17], v[130:131]
	v_pk_mul_f32 v[154:155], v[18:19], v[142:143]
	v_pk_fma_f32 v[148:149], v[12:13], v[126:127], v[148:149]
	v_pk_fma_f32 v[150:151], v[14:15], v[138:139], v[150:151]
	v_pk_fma_f32 v[152:153], v[12:13], v[128:129], v[152:153]
	v_pk_fma_f32 v[154:155], v[14:15], v[140:141], v[154:155]
	v_pk_fma_f32 v[148:149], v[8:9], v[124:125], v[148:149]
	v_pk_fma_f32 v[150:151], v[10:11], v[136:137], v[150:151]
	v_pk_fma_f32 v[152:153], v[8:9], v[126:127], v[152:153]
	v_pk_fma_f32 v[154:155], v[10:11], v[138:139], v[154:155]
	v_pk_mul_f32 v[148:149], v[148:149], v[132:133]
	v_pk_mul_f32 v[150:151], v[150:151], v[144:145]
	v_pk_mul_f32 v[152:153], v[152:153], v[134:135]
	v_pk_mul_f32 v[154:155], v[154:155], v[146:147]
	v_cvt_pk_bf16_f32 v164, v148, v149
	v_cvt_pk_bf16_f32 v165, v150, v151
	v_cvt_pk_bf16_f32 v166, v152, v153
	v_cvt_pk_bf16_f32 v167, v154, v155
	s_add_i32 s17, s16, 8
	s_lshl_b32 s17, s17, 2
	s_add_i32 s17, s17, 3
	s_lshl_b32 s17, s17, 17
	s_add_u32 s36, s40, s17
	s_addc_u32 s37, s41, 0
	global_store_dwordx2 v1, v[164:165], s[36:37]
	global_store_dwordx2 v1, v[166:167], s[36:37] offset:2048

; __device__ __forceinline__ int otid() { int t = threadIdx.x; asm volatile("" : "+v"(t)); return t; }
;     __device__ __forceinline__ bool next(int i, Unit& u) const { const long L = (long)i * G + c; if (L >= NG * 8) return false; u.g = (int)(L >> 3); u.pm = (int)(L & 7); u.pn = 0; return true; }
;     __device__ __forceinline__ bool next(int i, Unit& u) const { if (i >= 2) return false; u.g = g; u.pm = 2 * b + i; u.pn = 0; return true; }
; template <int MODE, class Sched> __device__ __forceinline__ void fixup_local(const bf16_t* halo, const float* cw, const float* cb, bf16_t* out, int C, const Sched& S) {
;     const int C4 = C >> 2, tid = otid(); Unit u;
;     for (int i = 0; S.next(i, u); ++i)
;         for (int c4 = tid; c4 < C4; c4 += 512) {
.Lfixs_generic:
	s_branch .LBB0_895
.LBB0_893:
	s_or_b64 exec, exec, s[8:9]
	s_add_i32 s50, s50, 1
	s_mov_b64 s[10:11], 0
